# v028-v026-plus-P3-fixup-32-loads-in-flight
# speedup vs baseline: 1.0010x; 1.0010x over previous
; __device__ __forceinline__ float bf_lo(unsigned w) { return __uint_as_float(w << 16); }
; __device__ __forceinline__ float bf_hi(unsigned w) { return __uint_as_float(w & 0xffff0000u); }
; template <int MODE> __device__ __forceinline__ void fix_resid(const float* part, int nsl, const float* xp, const float* xs, const float* meta, float* xbuf, bf16_t* xb, float* ss, float* out, int gw, int ngw, int lane) {
;     for (int it = gw; it < NTAIL * 8; it += ngw) {
;         const int rloc = it >> 3, row = TAIL0 + rloc, col = (it & 7) * 256 + lane * 4;
;         const bf16_t* p = (const bf16_t*)part + (size_t)rloc * 2048 + col;
;         f32x4_t v = (f32x4_t){0.f, 0.f, 0.f, 0.f};
; #pragma unroll 8
;         for (int s = 0; s < nsl; ++s) { const u32x2_t w = __builtin_nontemporal_load((const u32x2_t*)(p + (size_t)s * (256 * 2048))); v += (f32x4_t){bf_lo(w.x), bf_hi(w.x), bf_lo(w.y), bf_hi(w.y)}; }
.LBB0_445:
	s_lshl_b32 s6, s2, 1
	s_and_b32 s6, s6, 0xe00
	v_lshl_or_b32 v0, v241, 1, s6
	s_ashr_i32 s6, s14, 3
	s_ashr_i32 s7, s6, 31
	s_lshl_b64 s[18:19], s[6:7], 12
	s_add_u32 s18, s86, s18
	s_addc_u32 s19, s87, s19
	s_waitcnt lgkmcnt(0)
	v_mov_b32_e32 v6, 0
	v_mov_b32_e32 v7, v1
	v_mov_b32_e32 v8, 0
	v_mov_b32_e32 v9, v1
	global_load_dwordx2 v[32:33], v0, s[18:19] nt
	s_add_u32 s18, s18, 0x100000
	s_addc_u32 s19, s19, 0
	global_load_dwordx2 v[34:35], v0, s[18:19] nt
	s_add_u32 s18, s18, 0x100000
	s_addc_u32 s19, s19, 0
	global_load_dwordx2 v[36:37], v0, s[18:19] nt
	s_add_u32 s18, s18, 0x100000
	s_addc_u32 s19, s19, 0
	global_load_dwordx2 v[38:39], v0, s[18:19] nt
	s_add_u32 s18, s18, 0x100000
	s_addc_u32 s19, s19, 0
	global_load_dwordx2 v[40:41], v0, s[18:19] nt
	s_add_u32 s18, s18, 0x100000
	s_addc_u32 s19, s19, 0
	global_load_dwordx2 v[42:43], v0, s[18:19] nt
	s_add_u32 s18, s18, 0x100000
	s_addc_u32 s19, s19, 0
	global_load_dwordx2 v[44:45], v0, s[18:19] nt
	s_add_u32 s18, s18, 0x100000
	s_addc_u32 s19, s19, 0
	global_load_dwordx2 v[46:47], v0, s[18:19] nt
	s_add_u32 s18, s18, 0x100000
	s_addc_u32 s19, s19, 0
	global_load_dwordx2 v[48:49], v0, s[18:19] nt
	s_add_u32 s18, s18, 0x100000
	s_addc_u32 s19, s19, 0
	global_load_dwordx2 v[50:51], v0, s[18:19] nt
	s_add_u32 s18, s18, 0x100000
	s_addc_u32 s19, s19, 0
	global_load_dwordx2 v[52:53], v0, s[18:19] nt
	s_add_u32 s18, s18, 0x100000
	s_addc_u32 s19, s19, 0
	global_load_dwordx2 v[54:55], v0, s[18:19] nt
	s_add_u32 s18, s18, 0x100000
	s_addc_u32 s19, s19, 0
	global_load_dwordx2 v[56:57], v0, s[18:19] nt
	s_add_u32 s18, s18, 0x100000
	s_addc_u32 s19, s19, 0
	global_load_dwordx2 v[58:59], v0, s[18:19] nt
	s_add_u32 s18, s18, 0x100000
	s_addc_u32 s19, s19, 0
	global_load_dwordx2 v[60:61], v0, s[18:19] nt
	s_add_u32 s18, s18, 0x100000
	s_addc_u32 s19, s19, 0
	global_load_dwordx2 v[62:63], v0, s[18:19] nt
	s_add_u32 s18, s18, 0x100000
	s_addc_u32 s19, s19, 0
	global_load_dwordx2 v[64:65], v0, s[18:19] nt
	s_add_u32 s18, s18, 0x100000
	s_addc_u32 s19, s19, 0
	global_load_dwordx2 v[66:67], v0, s[18:19] nt
	s_add_u32 s18, s18, 0x100000
	s_addc_u32 s19, s19, 0
	global_load_dwordx2 v[68:69], v0, s[18:19] nt
	s_add_u32 s18, s18, 0x100000
	s_addc_u32 s19, s19, 0
	global_load_dwordx2 v[70:71], v0, s[18:19] nt
	s_add_u32 s18, s18, 0x100000
	s_addc_u32 s19, s19, 0
	global_load_dwordx2 v[72:73], v0, s[18:19] nt
	s_add_u32 s18, s18, 0x100000
	s_addc_u32 s19, s19, 0
	global_load_dwordx2 v[74:75], v0, s[18:19] nt
	s_add_u32 s18, s18, 0x100000
	s_addc_u32 s19, s19, 0
	global_load_dwordx2 v[76:77], v0, s[18:19] nt
	s_add_u32 s18, s18, 0x100000
	s_addc_u32 s19, s19, 0
	global_load_dwordx2 v[78:79], v0, s[18:19] nt
	s_add_u32 s18, s18, 0x100000
	s_addc_u32 s19, s19, 0
	global_load_dwordx2 v[80:81], v0, s[18:19] nt
	s_add_u32 s18, s18, 0x100000
	s_addc_u32 s19, s19, 0
	global_load_dwordx2 v[82:83], v0, s[18:19] nt
	s_add_u32 s18, s18, 0x100000
	s_addc_u32 s19, s19, 0
	global_load_dwordx2 v[84:85], v0, s[18:19] nt
	s_add_u32 s18, s18, 0x100000
	s_addc_u32 s19, s19, 0
	global_load_dwordx2 v[86:87], v0, s[18:19] nt
	s_add_u32 s18, s18, 0x100000
	s_addc_u32 s19, s19, 0
	global_load_dwordx2 v[88:89], v0, s[18:19] nt
	s_add_u32 s18, s18, 0x100000
	s_addc_u32 s19, s19, 0
	global_load_dwordx2 v[90:91], v0, s[18:19] nt
	s_add_u32 s18, s18, 0x100000
	s_addc_u32 s19, s19, 0
	global_load_dwordx2 v[92:93], v0, s[18:19] nt
	s_add_u32 s18, s18, 0x100000
	s_addc_u32 s19, s19, 0
	global_load_dwordx2 v[94:95], v0, s[18:19] nt
	s_waitcnt vmcnt(24)
	v_lshlrev_b32_e32 v20, 16, v32
	v_and_b32_e32 v21, 0xffff0000, v32
	v_lshlrev_b32_e32 v18, 16, v33
	v_and_b32_e32 v19, 0xffff0000, v33
	v_pk_add_f32 v[8:9], v[8:9], v[18:19]
	v_pk_add_f32 v[6:7], v[6:7], v[20:21]
	v_lshlrev_b32_e32 v20, 16, v34
	v_and_b32_e32 v21, 0xffff0000, v34
	v_lshlrev_b32_e32 v18, 16, v35
	v_and_b32_e32 v19, 0xffff0000, v35
	v_pk_add_f32 v[8:9], v[8:9], v[18:19]
	v_pk_add_f32 v[6:7], v[6:7], v[20:21]
	v_lshlrev_b32_e32 v20, 16, v36
	v_and_b32_e32 v21, 0xffff0000, v36
	v_lshlrev_b32_e32 v18, 16, v37
	v_and_b32_e32 v19, 0xffff0000, v37
	v_pk_add_f32 v[8:9], v[8:9], v[18:19]
	v_pk_add_f32 v[6:7], v[6:7], v[20:21]
	v_lshlrev_b32_e32 v20, 16, v38
	v_and_b32_e32 v21, 0xffff0000, v38
	v_lshlrev_b32_e32 v18, 16, v39
	v_and_b32_e32 v19, 0xffff0000, v39
	v_pk_add_f32 v[8:9], v[8:9], v[18:19]
	v_pk_add_f32 v[6:7], v[6:7], v[20:21]
	v_lshlrev_b32_e32 v20, 16, v40
	v_and_b32_e32 v21, 0xffff0000, v40
	v_lshlrev_b32_e32 v18, 16, v41
	v_and_b32_e32 v19, 0xffff0000, v41
	v_pk_add_f32 v[8:9], v[8:9], v[18:19]
	v_pk_add_f32 v[6:7], v[6:7], v[20:21]
	v_lshlrev_b32_e32 v20, 16, v42
	v_and_b32_e32 v21, 0xffff0000, v42
	v_lshlrev_b32_e32 v18, 16, v43
	v_and_b32_e32 v19, 0xffff0000, v43
	v_pk_add_f32 v[8:9], v[8:9], v[18:19]
	v_pk_add_f32 v[6:7], v[6:7], v[20:21]
	v_lshlrev_b32_e32 v20, 16, v44
	v_and_b32_e32 v21, 0xffff0000, v44
	v_lshlrev_b32_e32 v18, 16, v45
	v_and_b32_e32 v19, 0xffff0000, v45
	v_pk_add_f32 v[8:9], v[8:9], v[18:19]
	v_pk_add_f32 v[6:7], v[6:7], v[20:21]
	v_lshlrev_b32_e32 v20, 16, v46
	v_and_b32_e32 v21, 0xffff0000, v46
	v_lshlrev_b32_e32 v18, 16, v47
	v_and_b32_e32 v19, 0xffff0000, v47
	v_pk_add_f32 v[8:9], v[8:9], v[18:19]
	v_pk_add_f32 v[6:7], v[6:7], v[20:21]
	s_waitcnt vmcnt(16)
; __device__ __forceinline__ float bf_lo(unsigned w) { return __uint_as_float(w << 16); }
; __device__ __forceinline__ float bf_hi(unsigned w) { return __uint_as_float(w & 0xffff0000u); }
; template <int MODE> __device__ __forceinline__ void fix_resid(const float* part, int nsl, const float* xp, const float* xs, const float* meta, float* xbuf, bf16_t* xb, float* ss, float* out, int gw, int ngw, int lane) {
;     ...
;         for (int s = 0; s < nsl; ++s) { const u32x2_t w = __builtin_nontemporal_load((const u32x2_t*)(p + (size_t)s * (256 * 2048))); v += (f32x4_t){bf_lo(w.x), bf_hi(w.x), bf_lo(w.y), bf_hi(w.y)}; }
	v_lshlrev_b32_e32 v20, 16, v48
	v_and_b32_e32 v21, 0xffff0000, v48
	v_lshlrev_b32_e32 v18, 16, v49
	v_and_b32_e32 v19, 0xffff0000, v49
	v_pk_add_f32 v[8:9], v[8:9], v[18:19]
	v_pk_add_f32 v[6:7], v[6:7], v[20:21]
	v_lshlrev_b32_e32 v20, 16, v50
	v_and_b32_e32 v21, 0xffff0000, v50
	v_lshlrev_b32_e32 v18, 16, v51
	v_and_b32_e32 v19, 0xffff0000, v51
	v_pk_add_f32 v[8:9], v[8:9], v[18:19]
	v_pk_add_f32 v[6:7], v[6:7], v[20:21]
	v_lshlrev_b32_e32 v20, 16, v52
	v_and_b32_e32 v21, 0xffff0000, v52
	v_lshlrev_b32_e32 v18, 16, v53
	v_and_b32_e32 v19, 0xffff0000, v53
	v_pk_add_f32 v[8:9], v[8:9], v[18:19]
	v_pk_add_f32 v[6:7], v[6:7], v[20:21]
	v_lshlrev_b32_e32 v20, 16, v54
	v_and_b32_e32 v21, 0xffff0000, v54
	v_lshlrev_b32_e32 v18, 16, v55
	v_and_b32_e32 v19, 0xffff0000, v55
	v_pk_add_f32 v[8:9], v[8:9], v[18:19]
	v_pk_add_f32 v[6:7], v[6:7], v[20:21]
	v_lshlrev_b32_e32 v20, 16, v56
	v_and_b32_e32 v21, 0xffff0000, v56
	v_lshlrev_b32_e32 v18, 16, v57
	v_and_b32_e32 v19, 0xffff0000, v57
	v_pk_add_f32 v[8:9], v[8:9], v[18:19]
	v_pk_add_f32 v[6:7], v[6:7], v[20:21]
	v_lshlrev_b32_e32 v20, 16, v58
	v_and_b32_e32 v21, 0xffff0000, v58
	v_lshlrev_b32_e32 v18, 16, v59
	v_and_b32_e32 v19, 0xffff0000, v59
	v_pk_add_f32 v[8:9], v[8:9], v[18:19]
	v_pk_add_f32 v[6:7], v[6:7], v[20:21]
	v_lshlrev_b32_e32 v20, 16, v60
	v_and_b32_e32 v21, 0xffff0000, v60
	v_lshlrev_b32_e32 v18, 16, v61
	v_and_b32_e32 v19, 0xffff0000, v61
	v_pk_add_f32 v[8:9], v[8:9], v[18:19]
	v_pk_add_f32 v[6:7], v[6:7], v[20:21]
	v_lshlrev_b32_e32 v20, 16, v62
	v_and_b32_e32 v21, 0xffff0000, v62
	v_lshlrev_b32_e32 v18, 16, v63
	v_and_b32_e32 v19, 0xffff0000, v63
	v_pk_add_f32 v[8:9], v[8:9], v[18:19]
	v_pk_add_f32 v[6:7], v[6:7], v[20:21]
	s_waitcnt vmcnt(8)
	v_lshlrev_b32_e32 v20, 16, v64
	v_and_b32_e32 v21, 0xffff0000, v64
	v_lshlrev_b32_e32 v18, 16, v65
	v_and_b32_e32 v19, 0xffff0000, v65
	v_pk_add_f32 v[8:9], v[8:9], v[18:19]
	v_pk_add_f32 v[6:7], v[6:7], v[20:21]
	v_lshlrev_b32_e32 v20, 16, v66
	v_and_b32_e32 v21, 0xffff0000, v66
	v_lshlrev_b32_e32 v18, 16, v67
	v_and_b32_e32 v19, 0xffff0000, v67
	v_pk_add_f32 v[8:9], v[8:9], v[18:19]
	v_pk_add_f32 v[6:7], v[6:7], v[20:21]
	v_lshlrev_b32_e32 v20, 16, v68
	v_and_b32_e32 v21, 0xffff0000, v68
	v_lshlrev_b32_e32 v18, 16, v69
	v_and_b32_e32 v19, 0xffff0000, v69
	v_pk_add_f32 v[8:9], v[8:9], v[18:19]
	v_pk_add_f32 v[6:7], v[6:7], v[20:21]
	v_lshlrev_b32_e32 v20, 16, v70
	v_and_b32_e32 v21, 0xffff0000, v70
	v_lshlrev_b32_e32 v18, 16, v71
	v_and_b32_e32 v19, 0xffff0000, v71
	v_pk_add_f32 v[8:9], v[8:9], v[18:19]
	v_pk_add_f32 v[6:7], v[6:7], v[20:21]
	v_lshlrev_b32_e32 v20, 16, v72
	v_and_b32_e32 v21, 0xffff0000, v72
	v_lshlrev_b32_e32 v18, 16, v73
	v_and_b32_e32 v19, 0xffff0000, v73
	v_pk_add_f32 v[8:9], v[8:9], v[18:19]
	v_pk_add_f32 v[6:7], v[6:7], v[20:21]
	v_lshlrev_b32_e32 v20, 16, v74
	v_and_b32_e32 v21, 0xffff0000, v74
	v_lshlrev_b32_e32 v18, 16, v75
	v_and_b32_e32 v19, 0xffff0000, v75
	v_pk_add_f32 v[8:9], v[8:9], v[18:19]
	v_pk_add_f32 v[6:7], v[6:7], v[20:21]
	v_lshlrev_b32_e32 v20, 16, v76
	v_and_b32_e32 v21, 0xffff0000, v76
	v_lshlrev_b32_e32 v18, 16, v77
	v_and_b32_e32 v19, 0xffff0000, v77
	v_pk_add_f32 v[8:9], v[8:9], v[18:19]
	v_pk_add_f32 v[6:7], v[6:7], v[20:21]
	v_lshlrev_b32_e32 v20, 16, v78
	v_and_b32_e32 v21, 0xffff0000, v78
	v_lshlrev_b32_e32 v18, 16, v79
	v_and_b32_e32 v19, 0xffff0000, v79
	v_pk_add_f32 v[8:9], v[8:9], v[18:19]
	v_pk_add_f32 v[6:7], v[6:7], v[20:21]
	s_waitcnt vmcnt(0)
; __device__ __forceinline__ float bf_lo(unsigned w) { return __uint_as_float(w << 16); }
; __device__ __forceinline__ float bf_hi(unsigned w) { return __uint_as_float(w & 0xffff0000u); }
; __device__ __forceinline__ unsigned pk2(float lo, float hi) { return pg8::cvt_pk_bf16(lo, hi); }
; template <int MODE> __device__ __forceinline__ void fix_resid(const float* part, int nsl, const float* xp, const float* xs, const float* meta, float* xbuf, bf16_t* xb, float* ss, float* out, int gw, int ngw, int lane) {
;     ...
;         for (int s = 0; s < nsl; ++s) { const u32x2_t w = __builtin_nontemporal_load((const u32x2_t*)(p + (size_t)s * (256 * 2048))); v += (f32x4_t){bf_lo(w.x), bf_hi(w.x), bf_lo(w.y), bf_hi(w.y)}; }
;         const float scale = (MODE == 1) ? 1.0f : 0.5f;
;         const u32x2_t bw = *(const u32x2_t*)(xb + (size_t)row * DM + col);
;         const f32x4_t o = (f32x4_t){bf_lo(bw.x), bf_hi(bw.x), bf_lo(bw.y), bf_hi(bw.y)} + v * scale;
;         if (MODE == 2) { float* dst = y_row(out, row); if (dst) __builtin_nontemporal_store(o, (f32x4_t*)(dst + col)); }
;         else {
;             u32x2_t w; w.x = pk2(o.x, o.y); w.y = pk2(o.z, o.w); *(u32x2_t*)(xb + (size_t)row * DM + col) = w;
;             const float sq = wave_sum((o.x * o.x + o.y * o.y) + (o.z * o.z + o.w * o.w));
;             if (lane == 0) __hip_atomic_fetch_add(ss + row, sq, __ATOMIC_RELAXED, __HIP_MEMORY_SCOPE_AGENT);
;         }
	v_lshlrev_b32_e32 v20, 16, v80
	v_and_b32_e32 v21, 0xffff0000, v80
	v_lshlrev_b32_e32 v18, 16, v81
	v_and_b32_e32 v19, 0xffff0000, v81
	v_pk_add_f32 v[8:9], v[8:9], v[18:19]
	v_pk_add_f32 v[6:7], v[6:7], v[20:21]
	v_lshlrev_b32_e32 v20, 16, v82
	v_and_b32_e32 v21, 0xffff0000, v82
	v_lshlrev_b32_e32 v18, 16, v83
	v_and_b32_e32 v19, 0xffff0000, v83
	v_pk_add_f32 v[8:9], v[8:9], v[18:19]
	v_pk_add_f32 v[6:7], v[6:7], v[20:21]
	v_lshlrev_b32_e32 v20, 16, v84
	v_and_b32_e32 v21, 0xffff0000, v84
	v_lshlrev_b32_e32 v18, 16, v85
	v_and_b32_e32 v19, 0xffff0000, v85
	v_pk_add_f32 v[8:9], v[8:9], v[18:19]
	v_pk_add_f32 v[6:7], v[6:7], v[20:21]
	v_lshlrev_b32_e32 v20, 16, v86
	v_and_b32_e32 v21, 0xffff0000, v86
	v_lshlrev_b32_e32 v18, 16, v87
	v_and_b32_e32 v19, 0xffff0000, v87
	v_pk_add_f32 v[8:9], v[8:9], v[18:19]
	v_pk_add_f32 v[6:7], v[6:7], v[20:21]
	v_lshlrev_b32_e32 v20, 16, v88
	v_and_b32_e32 v21, 0xffff0000, v88
	v_lshlrev_b32_e32 v18, 16, v89
	v_and_b32_e32 v19, 0xffff0000, v89
	v_pk_add_f32 v[8:9], v[8:9], v[18:19]
	v_pk_add_f32 v[6:7], v[6:7], v[20:21]
	v_lshlrev_b32_e32 v20, 16, v90
	v_and_b32_e32 v21, 0xffff0000, v90
	v_lshlrev_b32_e32 v18, 16, v91
	v_and_b32_e32 v19, 0xffff0000, v91
	v_pk_add_f32 v[8:9], v[8:9], v[18:19]
	v_pk_add_f32 v[6:7], v[6:7], v[20:21]
	v_lshlrev_b32_e32 v20, 16, v92
	v_and_b32_e32 v21, 0xffff0000, v92
	v_lshlrev_b32_e32 v18, 16, v93
	v_and_b32_e32 v19, 0xffff0000, v93
	v_pk_add_f32 v[8:9], v[8:9], v[18:19]
	v_pk_add_f32 v[6:7], v[6:7], v[20:21]
	v_lshlrev_b32_e32 v20, 16, v94
	v_and_b32_e32 v21, 0xffff0000, v94
	v_lshlrev_b32_e32 v18, 16, v95
	v_and_b32_e32 v19, 0xffff0000, v95
	v_pk_add_f32 v[8:9], v[8:9], v[18:19]
	v_pk_add_f32 v[6:7], v[6:7], v[20:21]
	s_lshl_b32 s7, s14, 8
	s_and_b32 s7, s7, 0x700
	s_addk_i32 s6, 0x2000
	v_or_b32_e32 v0, s7, v241
	s_ashr_i32 s7, s6, 31
	s_lshl_b64 s[18:19], s[6:7], 12
	s_add_u32 s18, s96, s18
	s_addc_u32 s19, s97, s19
	v_lshlrev_b32_e32 v0, 1, v0
	global_load_dwordx2 v[2:3], v0, s[18:19]
	v_cmp_lt_i32_e32 vcc, v12, v11
	s_waitcnt vmcnt(0)
	v_lshlrev_b32_e32 v4, 16, v2
	v_and_b32_e32 v5, 0xffff0000, v2
	v_lshlrev_b32_e32 v2, 16, v3
	v_and_b32_e32 v3, 0xffff0000, v3
	v_pk_fma_f32 v[2:3], v[8:9], 0.5, v[2:3] op_sel_hi:[1,0,1]
	v_pk_fma_f32 v[4:5], v[6:7], 0.5, v[4:5] op_sel_hi:[1,0,1]
	s_nop 0
	v_cvt_pk_bf16_f32 v6, v4, v5
	v_cvt_pk_bf16_f32 v7, v2, v3
	global_store_dwordx2 v0, v[6:7], s[18:19]
	v_mul_f32_e32 v0, v5, v5
	v_mul_f32_e32 v3, v3, v3
	v_fmac_f32_e32 v0, v4, v4
	v_fmac_f32_e32 v3, v2, v2
	v_cndmask_b32_e32 v2, v10, v12, vcc
	v_add_f32_e32 v0, v0, v3
	v_lshlrev_b32_e32 v2, 2, v2
	ds_bpermute_b32 v2, v2, v0
	v_cmp_lt_i32_e32 vcc, v13, v11
	s_waitcnt lgkmcnt(0)
	v_add_f32_e32 v0, v0, v2
	v_cndmask_b32_e32 v2, v10, v13, vcc
	v_lshlrev_b32_e32 v2, 2, v2
	ds_bpermute_b32 v2, v2, v0
	v_cmp_lt_i32_e32 vcc, v14, v11
	s_waitcnt lgkmcnt(0)
	v_add_f32_e32 v0, v0, v2
	v_cndmask_b32_e32 v2, v10, v14, vcc
	v_lshlrev_b32_e32 v2, 2, v2
	ds_bpermute_b32 v2, v2, v0
	v_cmp_lt_i32_e32 vcc, v15, v11
	s_waitcnt lgkmcnt(0)
	v_add_f32_e32 v0, v0, v2
	v_cndmask_b32_e32 v2, v10, v15, vcc
	v_lshlrev_b32_e32 v2, 2, v2
	ds_bpermute_b32 v2, v2, v0
	v_cmp_lt_i32_e32 vcc, v16, v11
	s_waitcnt lgkmcnt(0)
	v_add_f32_e32 v0, v0, v2
	v_cndmask_b32_e32 v2, v10, v16, vcc
	v_lshlrev_b32_e32 v2, 2, v2
	ds_bpermute_b32 v2, v2, v0
	v_cmp_lt_i32_e32 vcc, v17, v11
	s_waitcnt lgkmcnt(0)
	v_add_f32_e32 v0, v0, v2
	v_cndmask_b32_e32 v2, v10, v17, vcc
	v_lshlrev_b32_e32 v2, 2, v2
	ds_bpermute_b32 v2, v2, v0
	s_mov_b64 s[18:19], exec
	v_readlane_b32 s20, v251, 31
	v_readlane_b32 s21, v251, 32
	s_and_b64 s[20:21], s[18:19], s[20:21]
	s_mov_b64 exec, s[20:21]
	s_cbranch_execz .LBB0_444
	s_mov_b64 s[20:21], exec
	s_waitcnt lgkmcnt(0)
	v_add_f32_e32 v2, v0, v2
	v_bfrev_b32_e32 v0, 1
